# barrier: acquire invalidate issued at arrival (overlaps the arrive atomic; CU idle until exit), no invalidate after the poll
# speedup vs baseline: 1.0272x; 1.0144x over previous
; __device__ __forceinline__ unsigned xb_add(unsigned* p, unsigned v) { return __hip_atomic_fetch_add(p, v, __ATOMIC_RELAXED, __HIP_MEMORY_SCOPE_AGENT); }
; __device__ __forceinline__ void xcd_barrier(const XcdBarrier& b, const bool is_t0) {
;     ...
;         __builtin_amdgcn_s_waitcnt(0);
;         unsigned nloc = b.st[0], nx = b.st[1];
;         if (nloc == 0u) { xcd_barrier_complete(bar, b.x, nloc, nx); b.st[0] = nloc; b.st[1] = nx; }
;         const unsigned old = xb_add(&bar[XB_XSUB(b.x)], 1u);
;         const unsigned gen = old / nloc;
;     ...
;             __builtin_amdgcn_fence(__ATOMIC_ACQUIRE, "agent");
.LBB0_463:
	s_lshl_b32 s2, s17, 8
	s_mov_b64 s[8:9], exec
	s_add_u32 s2, s74, s2
	s_addc_u32 s3, s75, 0
	v_mbcnt_lo_u32_b32 v1, s8, 0
	s_add_u32 s2, s2, 0x380000
	v_mbcnt_hi_u32_b32 v1, s9, v1
	s_addc_u32 s3, s3, 0
	v_cmp_eq_u32_e32 vcc, 0, v1
	s_and_saveexec_b64 s[18:19], vcc
	s_cbranch_execz .LBB0_465
	s_bcnt1_i32_b64 s8, s[8:9]
	v_mov_b32_e32 v3, s8
	buffer_inv sc1
	global_atomic_add v3, v200, v3, s[2:3] offset:1024 sc0

; __device__ __forceinline__ unsigned xb_ld(unsigned* p)              { return __hip_atomic_load(p, __ATOMIC_RELAXED, __HIP_MEMORY_SCOPE_AGENT); }
; #define XB_SPIN(cond, bar) do { unsigned _sp = 0; while (cond) { __builtin_amdgcn_s_sleep(1); \
;     if ((++_sp & 255u) == 0u) { if (xb_ld(&(bar)[XB_TMO])) break; if (_sp > XB_SPIN_CAP) { atomicAdd(&(bar)[XB_TMO], 1u); break; } } } } while (0)
; __device__ __forceinline__ void xcd_barrier(const XcdBarrier& b, const bool is_t0) {
;     ...
;             XB_SPIN(xb_ld(&bar[XB_XGEN(b.x)]) == gen, bar);
;             __builtin_amdgcn_fence(__ATOMIC_ACQUIRE, "agent");
;             asm volatile("s_waitcnt vmcnt(0)" ::: "memory");
;         }
;     }
;     __syncthreads();
; template <class FrameT>
; __device__ __forceinline__ void res_fixup(FrameT& F, const EpiRes& E, const pg8::DpSplit& S) {
;     const int nleft = S.nwg - S.G, tid = F.tid, wid = tid >> 6, lane = tid & 63, wr = wid >> 2, wc = wid & 3, fr = lane & 15, fq = lane >> 4;
;     for (int item = blockIdx.x; item < nleft * 8; item += F.G) {
.Lxb1_done:
.LBB0_499:
	s_or_b64 exec, exec, s[6:7]
	v_readlane_b32 s2, v253, 48
	v_readlane_b32 s3, v253, 49
	s_andn2_b64 vcc, exec, s[2:3]
	v_writelane_b32 v254, s85, 6
	s_waitcnt lgkmcnt(0)
	s_barrier
	s_cbranch_vccnz .LBB0_508
	v_ashrrev_i32_e32 v1, 2, v170
	v_and_b32_e32 v1, 0xffffffc0, v1
	v_and_or_b32 v22, v170, 15, v1
	v_lshrrev_b32_e32 v1, 1, v170
	v_bfe_u32 v0, v170, 4, 2
	v_and_b32_e32 v1, 0x60, v1
	v_lshlrev_b32_e32 v4, 2, v170
	v_lshl_or_b32 v23, v0, 3, v1
	v_ashrrev_i32_e32 v5, 31, v4
	v_cmp_eq_u32_e64 s[6:7], 0, v0
	v_mov_b32_e32 v6, v174
	v_mov_b32_e32 v7, v174
	s_mov_b32 s17, s64
	s_branch .LBB0_502

; __device__ __forceinline__ unsigned xb_add(unsigned* p, unsigned v) { return __hip_atomic_fetch_add(p, v, __ATOMIC_RELAXED, __HIP_MEMORY_SCOPE_AGENT); }
; __device__ __forceinline__ void xcd_barrier(const XcdBarrier& b, const bool is_t0) {
;     ...
;         __builtin_amdgcn_s_waitcnt(0);
;         unsigned nloc = b.st[0], nx = b.st[1];
;         if (nloc == 0u) { xcd_barrier_complete(bar, b.x, nloc, nx); b.st[0] = nloc; b.st[1] = nx; }
;         const unsigned old = xb_add(&bar[XB_XSUB(b.x)], 1u);
;         const unsigned gen = old / nloc;
;     ...
;             __builtin_amdgcn_fence(__ATOMIC_ACQUIRE, "agent");
.LBB0_616:
	s_lshl_b32 s2, s48, 8
	s_mov_b64 s[8:9], exec
	s_add_u32 s2, s6, s2
	s_addc_u32 s3, s7, 0
	v_mbcnt_lo_u32_b32 v1, s8, 0
	s_add_u32 s2, s2, 0x380000
	v_mbcnt_hi_u32_b32 v1, s9, v1
	s_addc_u32 s3, s3, 0
	v_cmp_eq_u32_e32 vcc, 0, v1
	s_and_saveexec_b64 s[10:11], vcc
	s_cbranch_execz .LBB0_618
	s_bcnt1_i32_b64 s8, s[8:9]
	v_mov_b32_e32 v3, s8
	buffer_inv sc1
	global_atomic_add v3, v200, v3, s[2:3] offset:1024 sc0

; __device__ __forceinline__ unsigned xb_ld(unsigned* p)              { return __hip_atomic_load(p, __ATOMIC_RELAXED, __HIP_MEMORY_SCOPE_AGENT); }
; #define XB_SPIN(cond, bar) do { unsigned _sp = 0; while (cond) { __builtin_amdgcn_s_sleep(1); \
;     if ((++_sp & 255u) == 0u) { if (xb_ld(&(bar)[XB_TMO])) break; if (_sp > XB_SPIN_CAP) { atomicAdd(&(bar)[XB_TMO], 1u); break; } } } } while (0)
; __device__ __forceinline__ void xcd_barrier(const XcdBarrier& b, const bool is_t0) {
;     ...
;             XB_SPIN(xb_ld(&bar[XB_XGEN(b.x)]) == gen, bar);
;             __builtin_amdgcn_fence(__ATOMIC_ACQUIRE, "agent");
;             asm volatile("s_waitcnt vmcnt(0)" ::: "memory");
;         }
;     }
;     __syncthreads();
.Lxb2_done:
	s_branch .LBB0_10
